# E14: help-mode claim issued one round ahead (atomic overlaps the conversion round), on top of E1+E2+E6
# baseline (speedup 1.0000x reference)
_Z6mk_fwd4Args:
	s_mov_b32 m0, 0
	s_load_dword s3, s[0:1], 0xd8
	s_add_u32 s4, s0, 0xd8
	v_writelane_b32 v252, s0, 0
	s_addc_u32 s5, s1, 0
	s_mov_b32 s97, s2
	v_writelane_b32 v252, s1, 1
	v_writelane_b32 v252, s4, 2
	s_waitcnt lgkmcnt(0)
	s_and_b32 s0, s3, 7
	s_cmp_lg_u32 s0, 0
	v_writelane_b32 v252, s5, 3
	s_mov_b32 s12, s2
	s_cbranch_scc1 .LBB0_2
	s_ashr_i32 s1, s97, 31
	s_lshr_b32 s1, s1, 29
	s_add_i32 s1, s97, s1
	s_and_b32 s2, s1, -8
	s_ashr_i32 s0, s3, 3
	s_sub_i32 s2, s97, s2
	s_mul_i32 s0, s0, s2
	s_ashr_i32 s1, s1, 3
	s_add_i32 s12, s0, s1

.LBB0_22:
	v_mov_b32_e32 v2, s72
	ds_read_b32 v2, v2
	s_waitcnt lgkmcnt(0)
	v_cmp_lt_u32_e32 vcc, s18, v2
	v_mov_b32_e32 v2, -1
	s_cbranch_vccnz .LBB0_28
	s_bitcmp1_b32 m0, 30
	s_cbranch_scc0 .Lgk_sync_0
	s_waitcnt vmcnt(0)
	v_mov_b32_e32 v3, v200
	v_mov_b32_e32 v2, 0
	s_bitset0_b32 m0, 30
	s_branch .Lgk_got_0
.Lgk_sync_0:
	s_mov_b64 s[6:7], exec
	v_mbcnt_lo_u32_b32 v2, s6, 0
	v_mbcnt_hi_u32_b32 v2, s7, v2
	v_cmp_eq_u32_e32 vcc, 0, v2
	s_and_saveexec_b64 s[4:5], vcc
	s_cbranch_execz .LBB0_26
	s_bcnt1_i32_b64 s2, s[6:7]
	s_lshl_b32 s2, s2, 3
	v_mov_b32_e32 v3, s2
	global_atomic_add v3, v67, v3, s[24:25] sc0

.Lgk_got_0:
	v_readfirstlane_b32 s2, v3
	s_nop 1
	v_lshl_add_u32 v2, v2, 3, s2
	v_add_u32_e32 v3, 8, v2
	v_cmp_lt_u32_e32 vcc, s18, v3
	s_cbranch_vccnz .Lgk_nopf_0
	v_mov_b32_e32 v200, 8
	global_atomic_add v200, v67, v200, s[24:25] sc0
	s_bitset1_b32 m0, 30
.Lgk_nopf_0:
.LBB0_27:
	v_mov_b32_e32 v4, s72
	ds_write_b32 v4, v3

.LBB0_317:
	v_readlane_b32 s2, v252, 24
	s_nop 1
	v_mov_b32_e32 v2, s2
	ds_read_b32 v2, v2
	s_waitcnt lgkmcnt(0)
	v_cmp_le_u32_e32 vcc, s24, v2
	v_mov_b32_e32 v2, -1
	s_cbranch_vccnz .LBB0_323
	s_bitcmp1_b32 m0, 30
	s_cbranch_scc0 .Lgk_sync_1
	s_waitcnt vmcnt(0)
	v_mov_b32_e32 v3, v200
	v_mov_b32_e32 v2, 0
	s_bitset0_b32 m0, 30
	s_branch .Lgk_got_1
.Lgk_sync_1:
	s_mov_b64 s[18:19], exec
	v_mbcnt_lo_u32_b32 v2, s18, 0
	v_mbcnt_hi_u32_b32 v2, s19, v2
	v_cmp_eq_u32_e32 vcc, 0, v2
	s_and_saveexec_b64 s[8:9], vcc
	s_cbranch_execz .LBB0_321
	s_bcnt1_i32_b64 s2, s[18:19]
	s_lshl_b32 s2, s2, 3
	v_mov_b32_e32 v3, s2
	global_atomic_add v3, v147, v3, s[34:35] sc0

.Lgk_got_1:
	v_readfirstlane_b32 s2, v3
	s_nop 1
	v_lshl_add_u32 v2, v2, 3, s2
	v_add_u32_e32 v3, 8, v2
	v_cmp_le_u32_e32 vcc, s24, v3
	s_cbranch_vccnz .Lgk_nopf_1
	v_mov_b32_e32 v200, 8
	global_atomic_add v200, v147, v200, s[34:35] sc0
	s_bitset1_b32 m0, 30
.Lgk_nopf_1:
.LBB0_322:
	v_readlane_b32 s2, v252, 24
	s_nop 1
	v_mov_b32_e32 v4, s2
	ds_write_b32 v4, v3

.LBB0_2465:
	v_readlane_b32 s2, v252, 24
	s_nop 1
	v_mov_b32_e32 v2, s2
	ds_read_b32 v2, v2
	s_waitcnt lgkmcnt(0)
	v_cmp_le_u32_e32 vcc, s15, v2
	v_mov_b32_e32 v2, -1
	s_cbranch_vccnz .LBB0_2471
	s_bitcmp1_b32 m0, 30
	s_cbranch_scc0 .Lgk_sync_8
	s_waitcnt vmcnt(0)
	v_mov_b32_e32 v3, v200
	v_mov_b32_e32 v2, 0
	s_bitset0_b32 m0, 30
	s_branch .Lgk_got_8

.Lgk_got_8:
	v_readfirstlane_b32 s2, v3
	s_nop 1
	v_lshl_add_u32 v2, v2, 3, s2
	v_add_u32_e32 v3, 8, v2
	v_cmp_le_u32_e32 vcc, s15, v3
	s_cbranch_vccnz .Lgk_nopf_8
	v_mov_b32_e32 v200, 8
	global_atomic_add v200, v147, v200, s[34:35] sc0
	s_bitset1_b32 m0, 30
